# v13: + P4 GEMM mainloop pipelined, attention epilogue with prefetched gates
# speedup vs baseline: 1.0861x; 1.0158x over previous
.Lattn_fast:
	s_add_i32 s16, s28, 0xfffffe00
	s_ashr_i32 s22, s28, 8
	s_lshr_b32 s8, s28, 2
	s_and_b32 s9, s28, 3
	s_lshr_b32 s16, s16, 7
	s_add_i32 s22, s22, 8
	s_cmpk_lt_i32 s28, 0x200
	s_cselect_b32 s24, 5, 4
	s_cselect_b32 s23, 31, 15
	s_cselect_b32 s16, s22, s16
	s_lshr_b32 s26, s28, s24
	s_and_b32 s8, s8, s23
	s_and_b32 s30, s26, 4
	s_or_b32 s27, s30, s9
	s_lshl_b32 s9, s16, 13
	s_lshl_b32 s8, s8, 8
	s_add_i32 s22, s9, 0xffff8000
	s_lshl_b32 s23, s16, 12
	s_add_i32 s29, s8, s18
	s_cmp_lt_i32 s16, 8
	s_cselect_b32 s8, s23, s22
	s_cselect_b32 s31, 12, 13
	s_add_i32 s29, s29, s8
	v_or_b32_e32 v0, s29, v189
	v_ashrrev_i32_e32 v1, 31, v0
	v_lshlrev_b64 v[0:1], 10, v[0:1]
	v_lshl_add_u64 v[0:1], s[62:63], 0, v[0:1]
	s_lshl_b32 s16, s27, 7
	v_lshl_add_u64 v[0:1], v[0:1], 0, s[16:17]
	v_lshlrev_b32_e32 v98, 1, v196
	v_lshl_add_u64 v[8:9], v[0:1], 0, v[98:99]
	s_lshl_b32 s26, s8, 8
	s_lshl_b32 s9, s30, 5
	s_add_u32 s9, s26, s9
	s_add_u32 s22, s64, s9
	s_addc_u32 s23, s65, 0
	s_add_i32 s9, s31, 5
	s_lshl_b32 s9, s30, s9
	s_add_u32 s9, s26, s9
	s_add_u32 s24, s72, s9
	s_addc_u32 s25, s73, 0
	v_lshl_add_u32 v210, v148, 8, v136
	s_add_i32 s9, s31, 1
	v_lshlrev_b32_e32 v211, s9, v148
	v_add_u32_e32 v211, v211, v136
	v_add_u32_e32 v206, v151, v156
	v_add_u32_e32 v207, v151, v157
	v_add_u32_e32 v208, v151, v158
	v_add_u32_e32 v209, v151, v159
	s_lshl_b32 s30, s27, 6
	s_lshl_b32 s33, 1, s31
	s_lshr_b32 s33, s33, 6
	s_add_i32 s16, s33, -1
	s_lshr_b32 s33, s33, 2
	s_mov_b32 s31, 5
	global_load_dwordx4 v[32:35], v210, s[22:23]
	s_add_u32 s26, s22, 0x4000
	s_addc_u32 s27, s23, 0
	global_load_dwordx4 v[36:39], v210, s[26:27]
	s_add_u32 s8, s22, 0x8000
	s_addc_u32 s9, s23, 0
	global_load_dwordx4 v[40:43], v210, s[8:9]
	global_load_dwordx4 v[44:47], v211, s[24:25]
	global_load_dwordx4 v[48:51], v211, s[24:25] offset:128
	global_load_dwordx4 v[74:77], v[8:9], off
	global_load_dwordx4 v[78:81], v[8:9], off offset:32
	global_load_dwordx4 v[82:85], v[8:9], off offset:64
	global_load_dwordx4 v[86:89], v[8:9], off offset:96
	s_add_u32 s26, s22, 0xc000
	s_addc_u32 s27, s23, 0
	global_load_dwordx4 v[90:93], v210, s[26:27]
	global_load_dwordx4 v[94:97], v211, s[24:25] offset:256
	s_add_u32 s8, s22, 0x10000
	s_addc_u32 s9, s23, 0
	global_load_dwordx4 v[250:253], v210, s[8:9]
	global_load_dwordx4 v[138:141], v211, s[24:25] offset:384
	v_mov_b32_e32 v72, 0
	v_mov_b32_e32 v73, 0
	v_mov_b32_e32 v16, 0
	v_mov_b32_e32 v17, 0
	v_mov_b32_e32 v18, 0
	v_mov_b32_e32 v19, 0
	v_mov_b32_e32 v20, 0
	v_mov_b32_e32 v21, 0
	v_mov_b32_e32 v22, 0
	v_mov_b32_e32 v23, 0
	v_mov_b32_e32 v24, 0
	v_mov_b32_e32 v25, 0
	v_mov_b32_e32 v26, 0
	v_mov_b32_e32 v27, 0
	v_mov_b32_e32 v28, 0
	v_mov_b32_e32 v29, 0
	v_mov_b32_e32 v30, 0
	v_mov_b32_e32 v31, 0
	v_mov_b32_e32 v0, 0
	v_mov_b32_e32 v1, 0
	v_mov_b32_e32 v2, 0
	v_mov_b32_e32 v3, 0
	v_mov_b32_e32 v4, 0
	v_mov_b32_e32 v5, 0
	v_mov_b32_e32 v6, 0
	v_mov_b32_e32 v7, 0
	v_mov_b32_e32 v8, 0
	v_mov_b32_e32 v9, 0
	v_mov_b32_e32 v10, 0
	v_mov_b32_e32 v11, 0
	v_mov_b32_e32 v12, 0
	v_mov_b32_e32 v13, 0
	v_mov_b32_e32 v14, 0
	v_mov_b32_e32 v15, 0
	s_waitcnt vmcnt(12)
	ds_write_b128 v150, v[32:35]
	s_waitcnt vmcnt(11)
	ds_write_b128 v150, v[36:39] offset:16384
	s_waitcnt vmcnt(10)
	ds_write_b128 v150, v[40:43] offset:32768
	s_waitcnt vmcnt(9)
	ds_write_b128 v150, v[44:47] offset:8192
	s_waitcnt vmcnt(8)
	ds_write_b128 v150, v[48:51] offset:24576
	s_waitcnt lgkmcnt(0)
	s_barrier
	ds_read_b128 v[218:221], v206
	ds_read_b128 v[226:229], v207
	ds_read_b128 v[234:237], v208
	s_waitcnt lgkmcnt(2)
	s_waitcnt vmcnt(7)
	v_mfma_f32_32x32x16_bf16 v[32:47], v[218:221], v[74:77], 0
	ds_read_b128 v[242:245], v209
	s_waitcnt lgkmcnt(2)
	s_waitcnt vmcnt(6)
	v_mfma_f32_32x32x16_bf16 v[32:47], v[226:229], v[78:81], v[32:47]
	ds_read_b128 v[218:221], v206 offset:4096
	s_waitcnt lgkmcnt(2)
	s_waitcnt vmcnt(5)
	v_mfma_f32_32x32x16_bf16 v[32:47], v[234:237], v[82:85], v[32:47]
	ds_read_b128 v[226:229], v207 offset:4096
	s_waitcnt lgkmcnt(2)
	s_waitcnt vmcnt(4)
	v_mfma_f32_32x32x16_bf16 v[32:47], v[242:245], v[86:89], v[32:47]
	ds_read_b128 v[234:237], v208 offset:4096
	s_nop 9
	s_waitcnt lgkmcnt(2)
	v_mfma_f32_32x32x16_bf16 v[48:63], v[218:221], v[74:77], 0
	ds_read_b128 v[242:245], v209 offset:4096
	v_exp_f32_e32 v32, v32
	v_exp_f32_e32 v33, v33
	v_add_f32_e32 v72, v72, v32
	v_add_f32_e32 v73, v73, v33
	v_cvt_pk_bf16_f32 v64, v32, v33
	v_exp_f32_e32 v34, v34
	v_exp_f32_e32 v35, v35
	s_waitcnt lgkmcnt(2)
	v_mfma_f32_32x32x16_bf16 v[48:63], v[226:229], v[78:81], v[48:63]
	ds_read_b128 v[218:221], v206 offset:16384
	v_add_f32_e32 v72, v72, v34
	v_add_f32_e32 v73, v73, v35
	v_cvt_pk_bf16_f32 v65, v34, v35
	v_exp_f32_e32 v36, v36
	v_exp_f32_e32 v37, v37
	ds_read_b128 v[222:225], v206 offset:8192
	v_add_f32_e32 v72, v72, v36
	v_add_f32_e32 v73, v73, v37
	v_cvt_pk_bf16_f32 v66, v36, v37
	v_exp_f32_e32 v38, v38
	v_exp_f32_e32 v39, v39
	s_waitcnt lgkmcnt(3)
	v_mfma_f32_32x32x16_bf16 v[48:63], v[234:237], v[82:85], v[48:63]
	ds_read_b128 v[226:229], v207 offset:16384
	v_add_f32_e32 v72, v72, v38
	v_add_f32_e32 v73, v73, v39
	v_cvt_pk_bf16_f32 v67, v38, v39
	v_exp_f32_e32 v40, v40
	v_exp_f32_e32 v41, v41
	ds_read_b128 v[230:233], v206 offset:12288
	v_add_f32_e32 v72, v72, v40
	v_add_f32_e32 v73, v73, v41
	v_cvt_pk_bf16_f32 v68, v40, v41
	v_exp_f32_e32 v42, v42
	v_exp_f32_e32 v43, v43
	s_waitcnt lgkmcnt(4)
	v_mfma_f32_32x32x16_bf16 v[48:63], v[242:245], v[86:89], v[48:63]
	ds_read_b128 v[234:237], v208 offset:16384
	v_add_f32_e32 v72, v72, v42
	v_add_f32_e32 v73, v73, v43
	v_cvt_pk_bf16_f32 v69, v42, v43
	v_exp_f32_e32 v44, v44
	v_exp_f32_e32 v45, v45
	ds_read_b128 v[238:241], v207 offset:8192
	v_add_f32_e32 v72, v72, v44
	v_add_f32_e32 v73, v73, v45
	v_cvt_pk_bf16_f32 v70, v44, v45
	v_exp_f32_e32 v46, v46
	v_exp_f32_e32 v47, v47
.Lattn_loop:
	v_add_f32_e32 v72, v72, v46
	v_add_f32_e32 v73, v73, v47
	v_cvt_pk_bf16_f32 v71, v46, v47
	s_waitcnt lgkmcnt(5)
	v_mfma_f32_32x32x16_bf16 v[32:47], v[218:221], v[74:77], 0
	ds_read_b128 v[242:245], v209 offset:16384
	v_exp_f32_e32 v48, v48
	v_exp_f32_e32 v49, v49
	s_waitcnt lgkmcnt(5)
	v_mfma_f32_32x32x16_bf16 v[16:31], v[222:225], v[64:67], v[16:31]
	ds_read_b128 v[246:249], v207 offset:12288
	s_waitcnt vmcnt(3)
	ds_write_b128 v150, v[90:93] offset:49152
	s_waitcnt vmcnt(2)
	ds_write_b128 v150, v[94:97] offset:40960
	v_add_f32_e32 v72, v72, v48
	v_add_f32_e32 v73, v73, v49
	v_cvt_pk_bf16_f32 v198, v48, v49
	v_exp_f32_e32 v50, v50
	v_exp_f32_e32 v51, v51
	s_waitcnt lgkmcnt(7)
	v_mfma_f32_32x32x16_bf16 v[32:47], v[226:229], v[78:81], v[32:47]
	ds_read_b128 v[218:221], v206 offset:20480
	v_add_f32_e32 v72, v72, v50
	v_add_f32_e32 v73, v73, v51
	v_cvt_pk_bf16_f32 v199, v50, v51
	v_exp_f32_e32 v52, v52
	v_exp_f32_e32 v53, v53
	s_waitcnt lgkmcnt(7)
	v_mfma_f32_32x32x16_bf16 v[0:15], v[230:233], v[64:67], v[0:15]
	ds_read_b128 v[222:225], v208 offset:8192
	s_min_u32 s8, s31, s16
	s_lshl_b32 s8, s8, 14
	s_add_u32 s26, s22, s8
	s_addc_u32 s27, s23, 0
	global_load_dwordx4 v[90:93], v210, s[26:27]
	s_add_i32 s9, s31, -1
	s_min_u32 s9, s9, s16
	s_lshl_b32 s9, s9, 7
	s_add_u32 s8, s24, s9
	s_addc_u32 s9, s25, 0
	global_load_dwordx4 v[94:97], v211, s[8:9]
	s_add_i32 s31, s31, 1
	v_add_f32_e32 v72, v72, v52
	v_add_f32_e32 v73, v73, v53
	v_cvt_pk_bf16_f32 v200, v52, v53
	v_exp_f32_e32 v54, v54
	v_exp_f32_e32 v55, v55
	s_waitcnt lgkmcnt(7)
	v_mfma_f32_32x32x16_bf16 v[32:47], v[234:237], v[82:85], v[32:47]
	ds_read_b128 v[226:229], v207 offset:20480
	v_add_f32_e32 v72, v72, v54
	v_add_f32_e32 v73, v73, v55
	v_cvt_pk_bf16_f32 v201, v54, v55
	v_exp_f32_e32 v56, v56
	v_exp_f32_e32 v57, v57
	s_waitcnt lgkmcnt(7)
	v_mfma_f32_32x32x16_bf16 v[16:31], v[238:241], v[68:71], v[16:31]
	ds_read_b128 v[230:233], v208 offset:12288
	v_add_f32_e32 v72, v72, v56
	v_add_f32_e32 v73, v73, v57
	v_cvt_pk_bf16_f32 v202, v56, v57
	v_exp_f32_e32 v58, v58
	v_exp_f32_e32 v59, v59
	s_waitcnt lgkmcnt(7)
	v_mfma_f32_32x32x16_bf16 v[32:47], v[242:245], v[86:89], v[32:47]
	ds_read_b128 v[234:237], v208 offset:20480
	v_add_f32_e32 v72, v72, v58
	v_add_f32_e32 v73, v73, v59
	v_cvt_pk_bf16_f32 v203, v58, v59
	v_exp_f32_e32 v60, v60
	v_exp_f32_e32 v61, v61
	s_waitcnt lgkmcnt(7)
	v_mfma_f32_32x32x16_bf16 v[0:15], v[246:249], v[68:71], v[0:15]
	ds_read_b128 v[238:241], v209 offset:8192
	v_add_f32_e32 v72, v72, v60
	v_add_f32_e32 v73, v73, v61
	v_cvt_pk_bf16_f32 v204, v60, v61
	v_exp_f32_e32 v62, v62
	v_exp_f32_e32 v63, v63
	v_add_f32_e32 v72, v72, v62
	v_add_f32_e32 v73, v73, v63
	v_cvt_pk_bf16_f32 v205, v62, v63
	s_waitcnt lgkmcnt(5)
	v_mfma_f32_32x32x16_bf16 v[48:63], v[218:221], v[74:77], 0
	ds_read_b128 v[242:245], v209 offset:20480
	v_exp_f32_e32 v32, v32
	v_exp_f32_e32 v33, v33
	s_waitcnt lgkmcnt(5)
	v_mfma_f32_32x32x16_bf16 v[16:31], v[222:225], v[198:201], v[16:31]
	ds_read_b128 v[246:249], v209 offset:12288
	v_add_f32_e32 v72, v72, v32
	v_add_f32_e32 v73, v73, v33
	v_cvt_pk_bf16_f32 v64, v32, v33
	v_exp_f32_e32 v34, v34
	v_exp_f32_e32 v35, v35
	s_waitcnt lgkmcnt(5)
	v_mfma_f32_32x32x16_bf16 v[48:63], v[226:229], v[78:81], v[48:63]
	ds_read_b128 v[218:221], v206 offset:32768
	v_add_f32_e32 v72, v72, v34
	v_add_f32_e32 v73, v73, v35
	v_cvt_pk_bf16_f32 v65, v34, v35
	v_exp_f32_e32 v36, v36
	v_exp_f32_e32 v37, v37
	s_waitcnt lgkmcnt(5)
	v_mfma_f32_32x32x16_bf16 v[0:15], v[230:233], v[198:201], v[0:15]
	ds_read_b128 v[222:225], v206 offset:24576
	v_add_f32_e32 v72, v72, v36
	v_add_f32_e32 v73, v73, v37
	v_cvt_pk_bf16_f32 v66, v36, v37
	v_exp_f32_e32 v38, v38
	v_exp_f32_e32 v39, v39
	s_waitcnt lgkmcnt(5)
	v_mfma_f32_32x32x16_bf16 v[48:63], v[234:237], v[82:85], v[48:63]
	ds_read_b128 v[226:229], v207 offset:32768
	v_add_f32_e32 v72, v72, v38
	v_add_f32_e32 v73, v73, v39
	v_cvt_pk_bf16_f32 v67, v38, v39
	v_exp_f32_e32 v40, v40
	v_exp_f32_e32 v41, v41
	s_waitcnt lgkmcnt(5)
	v_mfma_f32_32x32x16_bf16 v[16:31], v[238:241], v[202:205], v[16:31]
	ds_read_b128 v[230:233], v206 offset:28672
	v_add_f32_e32 v72, v72, v40
	v_add_f32_e32 v73, v73, v41
	v_cvt_pk_bf16_f32 v68, v40, v41
	v_exp_f32_e32 v42, v42
	v_exp_f32_e32 v43, v43
	s_waitcnt lgkmcnt(5)
	v_mfma_f32_32x32x16_bf16 v[48:63], v[242:245], v[86:89], v[48:63]
	ds_read_b128 v[234:237], v208 offset:32768
	v_add_f32_e32 v72, v72, v42
	v_add_f32_e32 v73, v73, v43
	v_cvt_pk_bf16_f32 v69, v42, v43
	v_exp_f32_e32 v44, v44
	v_exp_f32_e32 v45, v45
	s_waitcnt lgkmcnt(5)
	v_mfma_f32_32x32x16_bf16 v[0:15], v[246:249], v[202:205], v[0:15]
	ds_read_b128 v[238:241], v207 offset:24576
	v_add_f32_e32 v72, v72, v44
	v_add_f32_e32 v73, v73, v45
	v_cvt_pk_bf16_f32 v70, v44, v45
	v_exp_f32_e32 v46, v46
	v_exp_f32_e32 v47, v47
	s_barrier
	v_add_f32_e32 v72, v72, v46
	v_add_f32_e32 v73, v73, v47
	v_cvt_pk_bf16_f32 v71, v46, v47
	s_waitcnt lgkmcnt(5)
	v_mfma_f32_32x32x16_bf16 v[32:47], v[218:221], v[74:77], 0
	ds_read_b128 v[242:245], v209 offset:32768
	v_exp_f32_e32 v48, v48
	v_exp_f32_e32 v49, v49
	s_waitcnt lgkmcnt(5)
	v_mfma_f32_32x32x16_bf16 v[16:31], v[222:225], v[64:67], v[16:31]
	ds_read_b128 v[246:249], v207 offset:28672
	s_waitcnt vmcnt(3)
	ds_write_b128 v150, v[250:253]
	s_waitcnt vmcnt(2)
	ds_write_b128 v150, v[138:141] offset:57344
	v_add_f32_e32 v72, v72, v48
	v_add_f32_e32 v73, v73, v49
	v_cvt_pk_bf16_f32 v198, v48, v49
	v_exp_f32_e32 v50, v50
	v_exp_f32_e32 v51, v51
	s_waitcnt lgkmcnt(7)
	v_mfma_f32_32x32x16_bf16 v[32:47], v[226:229], v[78:81], v[32:47]
	ds_read_b128 v[218:221], v206 offset:36864
	v_add_f32_e32 v72, v72, v50
	v_add_f32_e32 v73, v73, v51
	v_cvt_pk_bf16_f32 v199, v50, v51
	v_exp_f32_e32 v52, v52
	v_exp_f32_e32 v53, v53
	s_waitcnt lgkmcnt(7)
	v_mfma_f32_32x32x16_bf16 v[0:15], v[230:233], v[64:67], v[0:15]
	ds_read_b128 v[222:225], v208 offset:24576
	s_min_u32 s8, s31, s16
	s_lshl_b32 s8, s8, 14
	s_add_u32 s26, s22, s8
	s_addc_u32 s27, s23, 0
	global_load_dwordx4 v[250:253], v210, s[26:27]
	s_add_i32 s9, s31, -1
	s_min_u32 s9, s9, s16
	s_lshl_b32 s9, s9, 7
	s_add_u32 s8, s24, s9
	s_addc_u32 s9, s25, 0
	global_load_dwordx4 v[138:141], v211, s[8:9]
	s_add_i32 s31, s31, 1
	v_add_f32_e32 v72, v72, v52
	v_add_f32_e32 v73, v73, v53
	v_cvt_pk_bf16_f32 v200, v52, v53
	v_exp_f32_e32 v54, v54
	v_exp_f32_e32 v55, v55
	s_waitcnt lgkmcnt(7)
	v_mfma_f32_32x32x16_bf16 v[32:47], v[234:237], v[82:85], v[32:47]
	ds_read_b128 v[226:229], v207 offset:36864
	v_add_f32_e32 v72, v72, v54
	v_add_f32_e32 v73, v73, v55
	v_cvt_pk_bf16_f32 v201, v54, v55
	v_exp_f32_e32 v56, v56
	v_exp_f32_e32 v57, v57
	s_waitcnt lgkmcnt(7)
	v_mfma_f32_32x32x16_bf16 v[16:31], v[238:241], v[68:71], v[16:31]
	ds_read_b128 v[230:233], v208 offset:28672
	v_add_f32_e32 v72, v72, v56
	v_add_f32_e32 v73, v73, v57
	v_cvt_pk_bf16_f32 v202, v56, v57
	v_exp_f32_e32 v58, v58
	v_exp_f32_e32 v59, v59
	s_waitcnt lgkmcnt(7)
	v_mfma_f32_32x32x16_bf16 v[32:47], v[242:245], v[86:89], v[32:47]
	ds_read_b128 v[234:237], v208 offset:36864
	v_add_f32_e32 v72, v72, v58
	v_add_f32_e32 v73, v73, v59
	v_cvt_pk_bf16_f32 v203, v58, v59
	v_exp_f32_e32 v60, v60
	v_exp_f32_e32 v61, v61
	s_waitcnt lgkmcnt(7)
	v_mfma_f32_32x32x16_bf16 v[0:15], v[246:249], v[68:71], v[0:15]
	ds_read_b128 v[238:241], v209 offset:24576
	v_add_f32_e32 v72, v72, v60
	v_add_f32_e32 v73, v73, v61
	v_cvt_pk_bf16_f32 v204, v60, v61
	v_exp_f32_e32 v62, v62
	v_exp_f32_e32 v63, v63
	v_add_f32_e32 v72, v72, v62
	v_add_f32_e32 v73, v73, v63
	v_cvt_pk_bf16_f32 v205, v62, v63
	s_waitcnt lgkmcnt(5)
	v_mfma_f32_32x32x16_bf16 v[48:63], v[218:221], v[74:77], 0
	ds_read_b128 v[242:245], v209 offset:36864
	v_exp_f32_e32 v32, v32
	v_exp_f32_e32 v33, v33
	s_waitcnt lgkmcnt(5)
	v_mfma_f32_32x32x16_bf16 v[16:31], v[222:225], v[198:201], v[16:31]
	ds_read_b128 v[246:249], v209 offset:28672
	v_add_f32_e32 v72, v72, v32
	v_add_f32_e32 v73, v73, v33
	v_cvt_pk_bf16_f32 v64, v32, v33
	v_exp_f32_e32 v34, v34
	v_exp_f32_e32 v35, v35
	s_waitcnt lgkmcnt(5)
	v_mfma_f32_32x32x16_bf16 v[48:63], v[226:229], v[78:81], v[48:63]
	ds_read_b128 v[218:221], v206 offset:49152
	v_add_f32_e32 v72, v72, v34
	v_add_f32_e32 v73, v73, v35
	v_cvt_pk_bf16_f32 v65, v34, v35
	v_exp_f32_e32 v36, v36
	v_exp_f32_e32 v37, v37
	s_waitcnt lgkmcnt(5)
	v_mfma_f32_32x32x16_bf16 v[0:15], v[230:233], v[198:201], v[0:15]
	ds_read_b128 v[222:225], v206 offset:40960
	v_add_f32_e32 v72, v72, v36
	v_add_f32_e32 v73, v73, v37
	v_cvt_pk_bf16_f32 v66, v36, v37
	v_exp_f32_e32 v38, v38
	v_exp_f32_e32 v39, v39
	s_waitcnt lgkmcnt(5)
	v_mfma_f32_32x32x16_bf16 v[48:63], v[234:237], v[82:85], v[48:63]
	ds_read_b128 v[226:229], v207 offset:49152
	v_add_f32_e32 v72, v72, v38
	v_add_f32_e32 v73, v73, v39
	v_cvt_pk_bf16_f32 v67, v38, v39
	v_exp_f32_e32 v40, v40
	v_exp_f32_e32 v41, v41
	s_waitcnt lgkmcnt(5)
	v_mfma_f32_32x32x16_bf16 v[16:31], v[238:241], v[202:205], v[16:31]
	ds_read_b128 v[230:233], v206 offset:45056
	v_add_f32_e32 v72, v72, v40
	v_add_f32_e32 v73, v73, v41
	v_cvt_pk_bf16_f32 v68, v40, v41
	v_exp_f32_e32 v42, v42
	v_exp_f32_e32 v43, v43
	s_waitcnt lgkmcnt(5)
	v_mfma_f32_32x32x16_bf16 v[48:63], v[242:245], v[86:89], v[48:63]
	ds_read_b128 v[234:237], v208 offset:49152
	v_add_f32_e32 v72, v72, v42
	v_add_f32_e32 v73, v73, v43
	v_cvt_pk_bf16_f32 v69, v42, v43
	v_exp_f32_e32 v44, v44
	v_exp_f32_e32 v45, v45
	s_waitcnt lgkmcnt(5)
	v_mfma_f32_32x32x16_bf16 v[0:15], v[246:249], v[202:205], v[0:15]
	ds_read_b128 v[238:241], v207 offset:40960
	v_add_f32_e32 v72, v72, v44
	v_add_f32_e32 v73, v73, v45
	v_cvt_pk_bf16_f32 v70, v44, v45
	v_exp_f32_e32 v46, v46
	v_exp_f32_e32 v47, v47
	s_barrier
	v_add_f32_e32 v72, v72, v46
	v_add_f32_e32 v73, v73, v47
	v_cvt_pk_bf16_f32 v71, v46, v47
	s_waitcnt lgkmcnt(5)
	v_mfma_f32_32x32x16_bf16 v[32:47], v[218:221], v[74:77], 0
	ds_read_b128 v[242:245], v209 offset:49152
	v_exp_f32_e32 v48, v48
	v_exp_f32_e32 v49, v49
	s_waitcnt lgkmcnt(5)
	v_mfma_f32_32x32x16_bf16 v[16:31], v[222:225], v[64:67], v[16:31]
	ds_read_b128 v[246:249], v207 offset:45056
	s_waitcnt vmcnt(3)
	ds_write_b128 v150, v[90:93] offset:16384
	s_waitcnt vmcnt(2)
	ds_write_b128 v150, v[94:97] offset:8192
	v_add_f32_e32 v72, v72, v48
	v_add_f32_e32 v73, v73, v49
	v_cvt_pk_bf16_f32 v198, v48, v49
	v_exp_f32_e32 v50, v50
	v_exp_f32_e32 v51, v51
	s_waitcnt lgkmcnt(7)
	v_mfma_f32_32x32x16_bf16 v[32:47], v[226:229], v[78:81], v[32:47]
	ds_read_b128 v[218:221], v206 offset:53248
	v_add_f32_e32 v72, v72, v50
	v_add_f32_e32 v73, v73, v51
	v_cvt_pk_bf16_f32 v199, v50, v51
	v_exp_f32_e32 v52, v52
	v_exp_f32_e32 v53, v53
	s_waitcnt lgkmcnt(7)
	v_mfma_f32_32x32x16_bf16 v[0:15], v[230:233], v[64:67], v[0:15]
	ds_read_b128 v[222:225], v208 offset:40960
	s_min_u32 s8, s31, s16
	s_lshl_b32 s8, s8, 14
	s_add_u32 s26, s22, s8
	s_addc_u32 s27, s23, 0
	global_load_dwordx4 v[90:93], v210, s[26:27]
	s_add_i32 s9, s31, -1
	s_min_u32 s9, s9, s16
	s_lshl_b32 s9, s9, 7
	s_add_u32 s8, s24, s9
	s_addc_u32 s9, s25, 0
	global_load_dwordx4 v[94:97], v211, s[8:9]
	s_add_i32 s31, s31, 1
	v_add_f32_e32 v72, v72, v52
	v_add_f32_e32 v73, v73, v53
	v_cvt_pk_bf16_f32 v200, v52, v53
	v_exp_f32_e32 v54, v54
	v_exp_f32_e32 v55, v55
	s_waitcnt lgkmcnt(7)
	v_mfma_f32_32x32x16_bf16 v[32:47], v[234:237], v[82:85], v[32:47]
	ds_read_b128 v[226:229], v207 offset:53248
	v_add_f32_e32 v72, v72, v54
	v_add_f32_e32 v73, v73, v55
	v_cvt_pk_bf16_f32 v201, v54, v55
	v_exp_f32_e32 v56, v56
	v_exp_f32_e32 v57, v57
	s_waitcnt lgkmcnt(7)
	v_mfma_f32_32x32x16_bf16 v[16:31], v[238:241], v[68:71], v[16:31]
	ds_read_b128 v[230:233], v208 offset:45056
	v_add_f32_e32 v72, v72, v56
	v_add_f32_e32 v73, v73, v57
	v_cvt_pk_bf16_f32 v202, v56, v57
	v_exp_f32_e32 v58, v58
	v_exp_f32_e32 v59, v59
	s_waitcnt lgkmcnt(7)
	v_mfma_f32_32x32x16_bf16 v[32:47], v[242:245], v[86:89], v[32:47]
	ds_read_b128 v[234:237], v208 offset:53248
	v_add_f32_e32 v72, v72, v58
	v_add_f32_e32 v73, v73, v59
	v_cvt_pk_bf16_f32 v203, v58, v59
	v_exp_f32_e32 v60, v60
	v_exp_f32_e32 v61, v61
	s_waitcnt lgkmcnt(7)
	v_mfma_f32_32x32x16_bf16 v[0:15], v[246:249], v[68:71], v[0:15]
	ds_read_b128 v[238:241], v209 offset:40960
	v_add_f32_e32 v72, v72, v60
	v_add_f32_e32 v73, v73, v61
	v_cvt_pk_bf16_f32 v204, v60, v61
	v_exp_f32_e32 v62, v62
	v_exp_f32_e32 v63, v63
	v_add_f32_e32 v72, v72, v62
	v_add_f32_e32 v73, v73, v63
	v_cvt_pk_bf16_f32 v205, v62, v63
	s_waitcnt lgkmcnt(5)
	v_mfma_f32_32x32x16_bf16 v[48:63], v[218:221], v[74:77], 0
	ds_read_b128 v[242:245], v209 offset:53248
	v_exp_f32_e32 v32, v32
	v_exp_f32_e32 v33, v33
	s_waitcnt lgkmcnt(5)
	v_mfma_f32_32x32x16_bf16 v[16:31], v[222:225], v[198:201], v[16:31]
	ds_read_b128 v[246:249], v209 offset:45056
	v_add_f32_e32 v72, v72, v32
	v_add_f32_e32 v73, v73, v33
	v_cvt_pk_bf16_f32 v64, v32, v33
	v_exp_f32_e32 v34, v34
	v_exp_f32_e32 v35, v35
	s_waitcnt lgkmcnt(5)
	v_mfma_f32_32x32x16_bf16 v[48:63], v[226:229], v[78:81], v[48:63]
	ds_read_b128 v[218:221], v206
	v_add_f32_e32 v72, v72, v34
	v_add_f32_e32 v73, v73, v35
	v_cvt_pk_bf16_f32 v65, v34, v35
	v_exp_f32_e32 v36, v36
	v_exp_f32_e32 v37, v37
	s_waitcnt lgkmcnt(5)
	v_mfma_f32_32x32x16_bf16 v[0:15], v[230:233], v[198:201], v[0:15]
	ds_read_b128 v[222:225], v206 offset:57344
	v_add_f32_e32 v72, v72, v36
	v_add_f32_e32 v73, v73, v37
	v_cvt_pk_bf16_f32 v66, v36, v37
	v_exp_f32_e32 v38, v38
	v_exp_f32_e32 v39, v39
	s_waitcnt lgkmcnt(5)
	v_mfma_f32_32x32x16_bf16 v[48:63], v[234:237], v[82:85], v[48:63]
	ds_read_b128 v[226:229], v207
	v_add_f32_e32 v72, v72, v38
	v_add_f32_e32 v73, v73, v39
	v_cvt_pk_bf16_f32 v67, v38, v39
	v_exp_f32_e32 v40, v40
	v_exp_f32_e32 v41, v41
	s_waitcnt lgkmcnt(5)
	v_mfma_f32_32x32x16_bf16 v[16:31], v[238:241], v[202:205], v[16:31]
	ds_read_b128 v[230:233], v206 offset:61440
	v_add_f32_e32 v72, v72, v40
	v_add_f32_e32 v73, v73, v41
	v_cvt_pk_bf16_f32 v68, v40, v41
	v_exp_f32_e32 v42, v42
	v_exp_f32_e32 v43, v43
	s_waitcnt lgkmcnt(5)
	v_mfma_f32_32x32x16_bf16 v[48:63], v[242:245], v[86:89], v[48:63]
	ds_read_b128 v[234:237], v208
	v_add_f32_e32 v72, v72, v42
	v_add_f32_e32 v73, v73, v43
	v_cvt_pk_bf16_f32 v69, v42, v43
	v_exp_f32_e32 v44, v44
	v_exp_f32_e32 v45, v45
	s_waitcnt lgkmcnt(5)
	v_mfma_f32_32x32x16_bf16 v[0:15], v[246:249], v[202:205], v[0:15]
	ds_read_b128 v[238:241], v207 offset:57344
	v_add_f32_e32 v72, v72, v44
	v_add_f32_e32 v73, v73, v45
	v_cvt_pk_bf16_f32 v70, v44, v45
	v_exp_f32_e32 v46, v46
	v_exp_f32_e32 v47, v47
	s_barrier
	s_add_i32 s33, s33, -1
	s_cmp_eq_u32 s33, 0
	s_cbranch_scc1 .Lattn_tail
	v_add_f32_e32 v72, v72, v46
	v_add_f32_e32 v73, v73, v47
	v_cvt_pk_bf16_f32 v71, v46, v47
	s_waitcnt lgkmcnt(5)
	v_mfma_f32_32x32x16_bf16 v[32:47], v[218:221], v[74:77], 0
	ds_read_b128 v[242:245], v209
	v_exp_f32_e32 v48, v48
	v_exp_f32_e32 v49, v49
	s_waitcnt lgkmcnt(5)
	v_mfma_f32_32x32x16_bf16 v[16:31], v[222:225], v[64:67], v[16:31]
	ds_read_b128 v[246:249], v207 offset:61440
	s_waitcnt vmcnt(3)
	ds_write_b128 v150, v[250:253] offset:32768
	s_waitcnt vmcnt(2)
	ds_write_b128 v150, v[138:141] offset:24576
	v_add_f32_e32 v72, v72, v48
	v_add_f32_e32 v73, v73, v49
	v_cvt_pk_bf16_f32 v198, v48, v49
	v_exp_f32_e32 v50, v50
	v_exp_f32_e32 v51, v51
	s_waitcnt lgkmcnt(7)
	v_mfma_f32_32x32x16_bf16 v[32:47], v[226:229], v[78:81], v[32:47]
	ds_read_b128 v[218:221], v206 offset:4096
	v_add_f32_e32 v72, v72, v50
	v_add_f32_e32 v73, v73, v51
	v_cvt_pk_bf16_f32 v199, v50, v51
	v_exp_f32_e32 v52, v52
	v_exp_f32_e32 v53, v53
	s_waitcnt lgkmcnt(7)
	v_mfma_f32_32x32x16_bf16 v[0:15], v[230:233], v[64:67], v[0:15]
	ds_read_b128 v[222:225], v208 offset:57344
	s_min_u32 s8, s31, s16
	s_lshl_b32 s8, s8, 14
	s_add_u32 s26, s22, s8
	s_addc_u32 s27, s23, 0
	global_load_dwordx4 v[250:253], v210, s[26:27]
	s_add_i32 s9, s31, -1
	s_min_u32 s9, s9, s16
	s_lshl_b32 s9, s9, 7
	s_add_u32 s8, s24, s9
	s_addc_u32 s9, s25, 0
	global_load_dwordx4 v[138:141], v211, s[8:9]
	s_add_i32 s31, s31, 1
	v_add_f32_e32 v72, v72, v52
	v_add_f32_e32 v73, v73, v53
	v_cvt_pk_bf16_f32 v200, v52, v53
	v_exp_f32_e32 v54, v54
	v_exp_f32_e32 v55, v55
	s_waitcnt lgkmcnt(7)
	v_mfma_f32_32x32x16_bf16 v[32:47], v[234:237], v[82:85], v[32:47]
	ds_read_b128 v[226:229], v207 offset:4096
	v_add_f32_e32 v72, v72, v54
	v_add_f32_e32 v73, v73, v55
	v_cvt_pk_bf16_f32 v201, v54, v55
	v_exp_f32_e32 v56, v56
	v_exp_f32_e32 v57, v57
	s_waitcnt lgkmcnt(7)
	v_mfma_f32_32x32x16_bf16 v[16:31], v[238:241], v[68:71], v[16:31]
	ds_read_b128 v[230:233], v208 offset:61440
	v_add_f32_e32 v72, v72, v56
	v_add_f32_e32 v73, v73, v57
	v_cvt_pk_bf16_f32 v202, v56, v57
	v_exp_f32_e32 v58, v58
	v_exp_f32_e32 v59, v59
	s_waitcnt lgkmcnt(7)
	v_mfma_f32_32x32x16_bf16 v[32:47], v[242:245], v[86:89], v[32:47]
	ds_read_b128 v[234:237], v208 offset:4096
	v_add_f32_e32 v72, v72, v58
	v_add_f32_e32 v73, v73, v59
	v_cvt_pk_bf16_f32 v203, v58, v59
	v_exp_f32_e32 v60, v60
	v_exp_f32_e32 v61, v61
	s_waitcnt lgkmcnt(7)
	v_mfma_f32_32x32x16_bf16 v[0:15], v[246:249], v[68:71], v[0:15]
	ds_read_b128 v[238:241], v209 offset:57344
	v_add_f32_e32 v72, v72, v60
	v_add_f32_e32 v73, v73, v61
	v_cvt_pk_bf16_f32 v204, v60, v61
	v_exp_f32_e32 v62, v62
	v_exp_f32_e32 v63, v63
	v_add_f32_e32 v72, v72, v62
	v_add_f32_e32 v73, v73, v63
	v_cvt_pk_bf16_f32 v205, v62, v63
	s_waitcnt lgkmcnt(5)
	v_mfma_f32_32x32x16_bf16 v[48:63], v[218:221], v[74:77], 0
	ds_read_b128 v[242:245], v209 offset:4096
	v_exp_f32_e32 v32, v32
	v_exp_f32_e32 v33, v33
	s_waitcnt lgkmcnt(5)
	v_mfma_f32_32x32x16_bf16 v[16:31], v[222:225], v[198:201], v[16:31]
	ds_read_b128 v[246:249], v209 offset:61440
	v_add_f32_e32 v72, v72, v32
	v_add_f32_e32 v73, v73, v33
	v_cvt_pk_bf16_f32 v64, v32, v33
	v_exp_f32_e32 v34, v34
	v_exp_f32_e32 v35, v35
	s_waitcnt lgkmcnt(5)
	v_mfma_f32_32x32x16_bf16 v[48:63], v[226:229], v[78:81], v[48:63]
	ds_read_b128 v[218:221], v206 offset:16384
	v_add_f32_e32 v72, v72, v34
	v_add_f32_e32 v73, v73, v35
	v_cvt_pk_bf16_f32 v65, v34, v35
	v_exp_f32_e32 v36, v36
	v_exp_f32_e32 v37, v37
	s_waitcnt lgkmcnt(5)
	v_mfma_f32_32x32x16_bf16 v[0:15], v[230:233], v[198:201], v[0:15]
	ds_read_b128 v[222:225], v206 offset:8192
	v_add_f32_e32 v72, v72, v36
	v_add_f32_e32 v73, v73, v37
	v_cvt_pk_bf16_f32 v66, v36, v37
	v_exp_f32_e32 v38, v38
	v_exp_f32_e32 v39, v39
	s_waitcnt lgkmcnt(5)
	v_mfma_f32_32x32x16_bf16 v[48:63], v[234:237], v[82:85], v[48:63]
	ds_read_b128 v[226:229], v207 offset:16384
	v_add_f32_e32 v72, v72, v38
	v_add_f32_e32 v73, v73, v39
	v_cvt_pk_bf16_f32 v67, v38, v39
	v_exp_f32_e32 v40, v40
	v_exp_f32_e32 v41, v41
	s_waitcnt lgkmcnt(5)
	v_mfma_f32_32x32x16_bf16 v[16:31], v[238:241], v[202:205], v[16:31]
	ds_read_b128 v[230:233], v206 offset:12288
	v_add_f32_e32 v72, v72, v40
	v_add_f32_e32 v73, v73, v41
	v_cvt_pk_bf16_f32 v68, v40, v41
	v_exp_f32_e32 v42, v42
	v_exp_f32_e32 v43, v43
	s_waitcnt lgkmcnt(5)
	v_mfma_f32_32x32x16_bf16 v[48:63], v[242:245], v[86:89], v[48:63]
	ds_read_b128 v[234:237], v208 offset:16384
	v_add_f32_e32 v72, v72, v42
	v_add_f32_e32 v73, v73, v43
	v_cvt_pk_bf16_f32 v69, v42, v43
	v_exp_f32_e32 v44, v44
	v_exp_f32_e32 v45, v45
	s_waitcnt lgkmcnt(5)
	v_mfma_f32_32x32x16_bf16 v[0:15], v[246:249], v[202:205], v[0:15]
	ds_read_b128 v[238:241], v207 offset:8192
	v_add_f32_e32 v72, v72, v44
	v_add_f32_e32 v73, v73, v45
	v_cvt_pk_bf16_f32 v70, v44, v45
	v_exp_f32_e32 v46, v46
	v_exp_f32_e32 v47, v47
	s_barrier
	s_branch .Lattn_loop
.Lattn_tail:
	s_lshl_b32 s16, s30, 1
	v_lshl_add_u64 v[186:187], v[102:103], 0, s[16:17]
	v_or_b32_e32 v210, s29, v152
	v_mov_b32_e32 v211, 0
	v_lshlrev_b64 v[210:211], 10, v[210:211]
	v_lshl_add_u64 v[210:211], v[186:187], 0, v[210:211]
	global_load_dwordx4 v[74:77], v[210:211], off
	v_or_b32_e32 v210, s29, v160
	v_mov_b32_e32 v211, 0
	v_lshlrev_b64 v[210:211], 10, v[210:211]
	v_lshl_add_u64 v[210:211], v[186:187], 0, v[210:211]
	global_load_dwordx4 v[78:81], v[210:211], off
	v_or_b32_e32 v210, s29, v161
	v_mov_b32_e32 v211, 0
	v_lshlrev_b64 v[210:211], 10, v[210:211]
	v_lshl_add_u64 v[210:211], v[186:187], 0, v[210:211]
	global_load_dwordx4 v[82:85], v[210:211], off
	v_or_b32_e32 v210, s29, v162
	v_mov_b32_e32 v211, 0
	v_lshlrev_b64 v[210:211], 10, v[210:211]
	v_lshl_add_u64 v[210:211], v[186:187], 0, v[210:211]
	global_load_dwordx4 v[86:89], v[210:211], off
	v_add_f32_e32 v72, v72, v46
	v_add_f32_e32 v73, v73, v47
	v_cvt_pk_bf16_f32 v71, v46, v47
	v_exp_f32_e32 v48, v48
	v_exp_f32_e32 v49, v49
	s_waitcnt lgkmcnt(4)
	v_mfma_f32_32x32x16_bf16 v[16:31], v[222:225], v[64:67], v[16:31]
	ds_read_b128 v[246:249], v207 offset:61440
	v_add_f32_e32 v72, v72, v48
	v_add_f32_e32 v73, v73, v49
	v_cvt_pk_bf16_f32 v198, v48, v49
	v_exp_f32_e32 v50, v50
	v_exp_f32_e32 v51, v51
	v_add_f32_e32 v72, v72, v50
	v_add_f32_e32 v73, v73, v51
	v_cvt_pk_bf16_f32 v199, v50, v51
	v_exp_f32_e32 v52, v52
	v_exp_f32_e32 v53, v53
	s_waitcnt lgkmcnt(3)
	v_mfma_f32_32x32x16_bf16 v[0:15], v[230:233], v[64:67], v[0:15]
	ds_read_b128 v[222:225], v208 offset:57344
	v_add_f32_e32 v72, v72, v52
	v_add_f32_e32 v73, v73, v53
	v_cvt_pk_bf16_f32 v200, v52, v53
	v_exp_f32_e32 v54, v54
	v_exp_f32_e32 v55, v55
	v_add_f32_e32 v72, v72, v54
	v_add_f32_e32 v73, v73, v55
	v_cvt_pk_bf16_f32 v201, v54, v55
	v_exp_f32_e32 v56, v56
	v_exp_f32_e32 v57, v57
	s_waitcnt lgkmcnt(2)
	v_mfma_f32_32x32x16_bf16 v[16:31], v[238:241], v[68:71], v[16:31]
	ds_read_b128 v[230:233], v208 offset:61440
	v_add_f32_e32 v72, v72, v56
	v_add_f32_e32 v73, v73, v57
	v_cvt_pk_bf16_f32 v202, v56, v57
	v_exp_f32_e32 v58, v58
	v_exp_f32_e32 v59, v59
	v_add_f32_e32 v72, v72, v58
	v_add_f32_e32 v73, v73, v59
	v_cvt_pk_bf16_f32 v203, v58, v59
	v_exp_f32_e32 v60, v60
	v_exp_f32_e32 v61, v61
	s_waitcnt lgkmcnt(2)
	v_mfma_f32_32x32x16_bf16 v[0:15], v[246:249], v[68:71], v[0:15]
	ds_read_b128 v[238:241], v209 offset:57344
	v_add_f32_e32 v72, v72, v60
	v_add_f32_e32 v73, v73, v61
	v_cvt_pk_bf16_f32 v204, v60, v61
	v_exp_f32_e32 v62, v62
	v_exp_f32_e32 v63, v63
	v_add_f32_e32 v72, v72, v62
	v_add_f32_e32 v73, v73, v63
	v_cvt_pk_bf16_f32 v205, v62, v63
	s_waitcnt lgkmcnt(2)
	v_mfma_f32_32x32x16_bf16 v[16:31], v[222:225], v[198:201], v[16:31]
	ds_read_b128 v[246:249], v209 offset:61440
	s_waitcnt lgkmcnt(2)
	v_mfma_f32_32x32x16_bf16 v[0:15], v[230:233], v[198:201], v[0:15]
	s_waitcnt lgkmcnt(1)
	v_mfma_f32_32x32x16_bf16 v[16:31], v[238:241], v[202:205], v[16:31]
	s_waitcnt lgkmcnt(0)
	v_mfma_f32_32x32x16_bf16 v[0:15], v[246:249], v[202:205], v[0:15]
	v_add_f32_e32 v72, v72, v73
	s_waitcnt vmcnt(0) lgkmcnt(0)
	s_barrier
	ds_bpermute_b32 v40, v147, v72
	v_lshl_add_u64 v[32:33], v[104:105], 0, s[16:17]
	s_waitcnt lgkmcnt(0)
	v_add_f32_e32 v40, v72, v40
	v_div_scale_f32 v41, s[8:9], v40, v40, 1.0
	v_rcp_f32_e32 v42, v41
	v_div_scale_f32 v43, vcc, 1.0, v40, 1.0
	v_fma_f32 v44, -v41, v42, 1.0
	v_fmac_f32_e32 v42, v44, v42
	v_mul_f32_e32 v44, v43, v42
	v_fma_f32 v45, -v41, v44, v43
	v_fmac_f32_e32 v44, v45, v42
	v_fma_f32 v41, -v41, v44, v43
	v_div_fmas_f32 v41, v41, v42, v44
	v_div_fixup_f32 v40, v41, v40, 1.0
	v_pk_mul_f32 v[16:17], v[40:41], v[16:17] op_sel_hi:[0,1]
	v_pk_mul_f32 v[18:19], v[40:41], v[18:19] op_sel_hi:[0,1]
	v_pk_mul_f32 v[20:21], v[40:41], v[20:21] op_sel_hi:[0,1]
	v_pk_mul_f32 v[22:23], v[40:41], v[22:23] op_sel_hi:[0,1]
	v_pk_mul_f32 v[24:25], v[40:41], v[24:25] op_sel_hi:[0,1]
	v_pk_mul_f32 v[26:27], v[40:41], v[26:27] op_sel_hi:[0,1]
	v_pk_mul_f32 v[28:29], v[40:41], v[28:29] op_sel_hi:[0,1]
	v_pk_mul_f32 v[30:31], v[40:41], v[30:31] op_sel_hi:[0,1]
	v_pk_mul_f32 v[0:1], v[40:41], v[0:1] op_sel_hi:[0,1]
	v_pk_mul_f32 v[2:3], v[40:41], v[2:3] op_sel_hi:[0,1]
	v_pk_mul_f32 v[4:5], v[40:41], v[4:5] op_sel_hi:[0,1]
	v_pk_mul_f32 v[6:7], v[40:41], v[6:7] op_sel_hi:[0,1]
	v_pk_mul_f32 v[8:9], v[40:41], v[8:9] op_sel_hi:[0,1]
	v_pk_mul_f32 v[10:11], v[40:41], v[10:11] op_sel_hi:[0,1]
	v_pk_mul_f32 v[12:13], v[40:41], v[12:13] op_sel_hi:[0,1]
	v_pk_mul_f32 v[14:15], v[40:41], v[14:15] op_sel_hi:[0,1]
	v_cvt_pk_bf16_f32 v16, v16, v17
	v_cvt_pk_bf16_f32 v17, v18, v19
	v_cvt_pk_bf16_f32 v18, v20, v21
	v_cvt_pk_bf16_f32 v19, v22, v23
	v_cvt_pk_bf16_f32 v20, v24, v25
	v_cvt_pk_bf16_f32 v21, v26, v27
	v_cvt_pk_bf16_f32 v22, v28, v29
	v_cvt_pk_bf16_f32 v23, v30, v31
	v_cvt_pk_bf16_f32 v0, v0, v1
	v_cvt_pk_bf16_f32 v1, v2, v3
	v_cvt_pk_bf16_f32 v2, v4, v5
	v_cvt_pk_bf16_f32 v3, v6, v7
	v_cvt_pk_bf16_f32 v4, v8, v9
	v_cvt_pk_bf16_f32 v5, v10, v11
	v_cvt_pk_bf16_f32 v6, v12, v13
	v_cvt_pk_bf16_f32 v7, v14, v15
	ds_write_b64 v171, v[16:17]
	ds_write_b64 v172, v[18:19]
	ds_write_b64 v173, v[20:21]
	ds_write_b64 v174, v[22:23]
	ds_write_b64 v175, v[0:1]
	ds_write_b64 v176, v[2:3]
	ds_write_b64 v177, v[4:5]
	ds_write_b64 v178, v[6:7]
	ds_read_b128 v[8:11], v179
	ds_read_b128 v[12:15], v180
	ds_read_b128 v[24:27], v181
	ds_read_b128 v[28:31], v182
	s_waitcnt lgkmcnt(3)
	v_cndmask_b32_e64 v46, v10, v8, s[6:7]
	v_cndmask_b32_e64 v47, v11, v9, s[6:7]
	v_cndmask_b32_e64 v48, v8, v10, s[6:7]
	v_cndmask_b32_e64 v49, v9, v11, s[6:7]
	v_lshlrev_b32_e32 v50, 16, v46
	v_and_b32_e32 v51, 0xffff0000, v46
	v_lshlrev_b32_e32 v52, 16, v74
	v_and_b32_e32 v53, 0xffff0000, v74
	v_pk_mul_f32 v[50:51], v[52:53], v[50:51]
	v_cvt_pk_bf16_f32 v54, v50, v51
	v_lshlrev_b32_e32 v50, 16, v47
	v_and_b32_e32 v51, 0xffff0000, v47
	v_lshlrev_b32_e32 v52, 16, v75
	v_and_b32_e32 v53, 0xffff0000, v75
	v_pk_mul_f32 v[50:51], v[52:53], v[50:51]
	v_cvt_pk_bf16_f32 v55, v50, v51
	v_lshlrev_b32_e32 v50, 16, v48
	v_and_b32_e32 v51, 0xffff0000, v48
	v_lshlrev_b32_e32 v52, 16, v76
	v_and_b32_e32 v53, 0xffff0000, v76
	v_pk_mul_f32 v[50:51], v[52:53], v[50:51]
	v_cvt_pk_bf16_f32 v56, v50, v51
	v_lshlrev_b32_e32 v50, 16, v49
	v_and_b32_e32 v51, 0xffff0000, v49
	v_lshlrev_b32_e32 v52, 16, v77
	v_and_b32_e32 v53, 0xffff0000, v77
	v_pk_mul_f32 v[50:51], v[52:53], v[50:51]
	v_cvt_pk_bf16_f32 v57, v50, v51
	v_or_b32_e32 v60, s29, v152
	v_mov_b32_e32 v61, 0
	v_lshlrev_b64 v[60:61], 11, v[60:61]
	v_lshl_add_u64 v[58:59], v[32:33], 0, v[60:61]
	global_store_dwordx4 v[58:59], v[54:57], off
	s_nop 1
	s_waitcnt lgkmcnt(2)
	v_cndmask_b32_e64 v46, v14, v12, s[6:7]
	v_cndmask_b32_e64 v47, v15, v13, s[6:7]
	v_cndmask_b32_e64 v48, v12, v14, s[6:7]
	v_cndmask_b32_e64 v49, v13, v15, s[6:7]
	v_lshlrev_b32_e32 v50, 16, v46
	v_and_b32_e32 v51, 0xffff0000, v46
	v_lshlrev_b32_e32 v52, 16, v78
	v_and_b32_e32 v53, 0xffff0000, v78
	v_pk_mul_f32 v[50:51], v[52:53], v[50:51]
	v_cvt_pk_bf16_f32 v54, v50, v51
	v_lshlrev_b32_e32 v50, 16, v47
	v_and_b32_e32 v51, 0xffff0000, v47
	v_lshlrev_b32_e32 v52, 16, v79
	v_and_b32_e32 v53, 0xffff0000, v79
	v_pk_mul_f32 v[50:51], v[52:53], v[50:51]
	v_cvt_pk_bf16_f32 v55, v50, v51
	v_lshlrev_b32_e32 v50, 16, v48
	v_and_b32_e32 v51, 0xffff0000, v48
	v_lshlrev_b32_e32 v52, 16, v80
	v_and_b32_e32 v53, 0xffff0000, v80
	v_pk_mul_f32 v[50:51], v[52:53], v[50:51]
	v_cvt_pk_bf16_f32 v56, v50, v51
	v_lshlrev_b32_e32 v50, 16, v49
	v_and_b32_e32 v51, 0xffff0000, v49
	v_lshlrev_b32_e32 v52, 16, v81
	v_and_b32_e32 v53, 0xffff0000, v81
	v_pk_mul_f32 v[50:51], v[52:53], v[50:51]
	v_cvt_pk_bf16_f32 v57, v50, v51
	v_or_b32_e32 v60, s29, v160
	v_mov_b32_e32 v61, 0
	v_lshlrev_b64 v[60:61], 11, v[60:61]
	v_lshl_add_u64 v[58:59], v[32:33], 0, v[60:61]
	global_store_dwordx4 v[58:59], v[54:57], off
	s_nop 1
	s_waitcnt lgkmcnt(1)
	v_cndmask_b32_e64 v46, v26, v24, s[6:7]
	v_cndmask_b32_e64 v47, v27, v25, s[6:7]
	v_cndmask_b32_e64 v48, v24, v26, s[6:7]
	v_cndmask_b32_e64 v49, v25, v27, s[6:7]
	v_lshlrev_b32_e32 v50, 16, v46
	v_and_b32_e32 v51, 0xffff0000, v46
	v_lshlrev_b32_e32 v52, 16, v82
	v_and_b32_e32 v53, 0xffff0000, v82
	v_pk_mul_f32 v[50:51], v[52:53], v[50:51]
	v_cvt_pk_bf16_f32 v54, v50, v51
	v_lshlrev_b32_e32 v50, 16, v47
	v_and_b32_e32 v51, 0xffff0000, v47
	v_lshlrev_b32_e32 v52, 16, v83
	v_and_b32_e32 v53, 0xffff0000, v83
	v_pk_mul_f32 v[50:51], v[52:53], v[50:51]
	v_cvt_pk_bf16_f32 v55, v50, v51
	v_lshlrev_b32_e32 v50, 16, v48
	v_and_b32_e32 v51, 0xffff0000, v48
	v_lshlrev_b32_e32 v52, 16, v84
	v_and_b32_e32 v53, 0xffff0000, v84
	v_pk_mul_f32 v[50:51], v[52:53], v[50:51]
	v_cvt_pk_bf16_f32 v56, v50, v51
	v_lshlrev_b32_e32 v50, 16, v49
	v_and_b32_e32 v51, 0xffff0000, v49
	v_lshlrev_b32_e32 v52, 16, v85
	v_and_b32_e32 v53, 0xffff0000, v85
	v_pk_mul_f32 v[50:51], v[52:53], v[50:51]
	v_cvt_pk_bf16_f32 v57, v50, v51
	v_or_b32_e32 v60, s29, v161
	v_mov_b32_e32 v61, 0
	v_lshlrev_b64 v[60:61], 11, v[60:61]
	v_lshl_add_u64 v[58:59], v[32:33], 0, v[60:61]
	global_store_dwordx4 v[58:59], v[54:57], off
	s_nop 1
	s_waitcnt lgkmcnt(0)
	v_cndmask_b32_e64 v46, v30, v28, s[6:7]
	v_cndmask_b32_e64 v47, v31, v29, s[6:7]
	v_cndmask_b32_e64 v48, v28, v30, s[6:7]
	v_cndmask_b32_e64 v49, v29, v31, s[6:7]
	v_lshlrev_b32_e32 v50, 16, v46
	v_and_b32_e32 v51, 0xffff0000, v46
	v_lshlrev_b32_e32 v52, 16, v86
	v_and_b32_e32 v53, 0xffff0000, v86
	v_pk_mul_f32 v[50:51], v[52:53], v[50:51]
	v_cvt_pk_bf16_f32 v54, v50, v51
	v_lshlrev_b32_e32 v50, 16, v47
	v_and_b32_e32 v51, 0xffff0000, v47
	v_lshlrev_b32_e32 v52, 16, v87
	v_and_b32_e32 v53, 0xffff0000, v87
	v_pk_mul_f32 v[50:51], v[52:53], v[50:51]
	v_cvt_pk_bf16_f32 v55, v50, v51
	v_lshlrev_b32_e32 v50, 16, v48
	v_and_b32_e32 v51, 0xffff0000, v48
	v_lshlrev_b32_e32 v52, 16, v88
	v_and_b32_e32 v53, 0xffff0000, v88
	v_pk_mul_f32 v[50:51], v[52:53], v[50:51]
	v_cvt_pk_bf16_f32 v56, v50, v51
	v_lshlrev_b32_e32 v50, 16, v49
	v_and_b32_e32 v51, 0xffff0000, v49
	v_lshlrev_b32_e32 v52, 16, v89
	v_and_b32_e32 v53, 0xffff0000, v89
	v_pk_mul_f32 v[50:51], v[52:53], v[50:51]
	v_cvt_pk_bf16_f32 v57, v50, v51
	v_or_b32_e32 v60, s29, v162
	v_mov_b32_e32 v61, 0
	v_lshlrev_b64 v[60:61], 11, v[60:61]
	v_lshl_add_u64 v[58:59], v[32:33], 0, v[60:61]
	global_store_dwordx4 v[58:59], v[54:57], off
	s_nop 1
	s_branch .LBB0_299

.LBB0_374:
	s_and_b32 s64, s33, 3
	s_and_b32 s65, s75, 3
	s_lshl_b32 s68, s64, 9
	s_ashr_i32 s64, s75, 2
	s_lshl_b32 s65, s65, 19
	s_add_u32 s66, s70, s65
	s_addc_u32 s67, s71, 0
	s_ashr_i32 s65, s64, 31
	s_lshl_b64 s[64:65], s[64:65], 19
	s_add_u32 s70, s0, s64
	v_readfirstlane_b32 s69, v191
	s_addc_u32 s71, s1, s65
	s_lshr_b32 s76, s69, 6
	v_lshl_or_b32 v198, s76, 4, v193
	v_lshlrev_b32_e32 v198, 11, v198
	v_add_u32_e32 v198, v198, v134
	v_add_u32_e32 v199, 0x40000, v198
	s_lshl_b32 s72, s76, 10
	s_lshr_b32 s77, s69, 1
	s_and_b32 s77, s77, 0x3ffff80
	v_or_b32_e32 v200, s77, v189
	v_lshlrev_b32_e32 v200, 6, v200
	s_and_b32 s77, s69, 0xc0
	v_or_b32_e32 v201, s77, v189
	v_lshlrev_b32_e32 v201, 6, v201
	v_add_u32_e32 v246, v200, v140
	v_add_u32_e32 v247, v200, v141
	v_add_u32_e32 v248, v201, v140
	v_add_u32_e32 v249, v201, v141
	v_add_u32_e32 v250, 0x10000, v246
	v_add_u32_e32 v251, 0x10000, v247
	v_add_u32_e32 v252, 0x10000, v248
	v_add_u32_e32 v253, 0x10000, v249
	s_add_i32 m0, s72, 0x0
	s_nop 0
	global_load_lds_dwordx4 v198, s[66:67]
	s_add_i32 m0, s72, 0x4000
	s_nop 0
	global_load_lds_dwordx4 v198, s[70:71]
	s_add_i32 m0, s72, 0x2000
	s_nop 0
	global_load_lds_dwordx4 v199, s[66:67]
	s_add_i32 m0, s72, 0x6000
	s_nop 0
	global_load_lds_dwordx4 v199, s[70:71]
	s_add_u32 s66, s66, 64
	s_addc_u32 s67, s67, 0
	s_add_u32 s70, s70, 64
	s_addc_u32 s71, s71, 0
	s_add_i32 m0, s72, 0x8000
	s_nop 0
	global_load_lds_dwordx4 v198, s[66:67]
	s_add_i32 m0, s72, 0xc000
	s_nop 0
	global_load_lds_dwordx4 v198, s[70:71]
	s_add_i32 m0, s72, 0xa000
	s_nop 0
	global_load_lds_dwordx4 v199, s[66:67]
	s_add_i32 m0, s72, 0xe000
	s_nop 0
	global_load_lds_dwordx4 v199, s[70:71]
	s_add_u32 s66, s66, 64
	s_addc_u32 s67, s67, 0
	s_add_u32 s70, s70, 64
	s_addc_u32 s71, s71, 0
	s_add_i32 m0, s72, 0x10000
	s_nop 0
	global_load_lds_dwordx4 v198, s[66:67]
	s_add_i32 m0, s72, 0x14000
	s_nop 0
	global_load_lds_dwordx4 v198, s[70:71]
	s_add_i32 m0, s72, 0x12000
	s_nop 0
	global_load_lds_dwordx4 v199, s[66:67]
	s_add_i32 m0, s72, 0x16000
	s_nop 0
	global_load_lds_dwordx4 v199, s[70:71]
	s_add_u32 s66, s66, 64
	s_addc_u32 s67, s67, 0
	s_add_u32 s70, s70, 64
	s_addc_u32 s71, s71, 0
	v_mov_b32_e32 v112, 0
	v_mov_b32_e32 v113, 0
	v_mov_b32_e32 v114, 0
	v_mov_b32_e32 v115, 0
	v_mov_b32_e32 v116, 0
	v_mov_b32_e32 v117, 0
	v_mov_b32_e32 v118, 0
	v_mov_b32_e32 v119, 0
	v_mov_b32_e32 v120, 0
	v_mov_b32_e32 v121, 0
	v_mov_b32_e32 v122, 0
	v_mov_b32_e32 v123, 0
	v_mov_b32_e32 v124, 0
	v_mov_b32_e32 v125, 0
	v_mov_b32_e32 v126, 0
	v_mov_b32_e32 v127, 0
	v_mov_b32_e32 v48, 0
	v_mov_b32_e32 v49, 0
	v_mov_b32_e32 v50, 0
	v_mov_b32_e32 v51, 0
	v_mov_b32_e32 v52, 0
	v_mov_b32_e32 v53, 0
	v_mov_b32_e32 v54, 0
	v_mov_b32_e32 v55, 0
	v_mov_b32_e32 v56, 0
	v_mov_b32_e32 v57, 0
	v_mov_b32_e32 v58, 0
	v_mov_b32_e32 v59, 0
	v_mov_b32_e32 v60, 0
	v_mov_b32_e32 v61, 0
	v_mov_b32_e32 v62, 0
	v_mov_b32_e32 v63, 0
	v_mov_b32_e32 v96, 0
	v_mov_b32_e32 v97, 0
	v_mov_b32_e32 v98, 0
	v_mov_b32_e32 v99, 0
	v_mov_b32_e32 v100, 0
	v_mov_b32_e32 v101, 0
	v_mov_b32_e32 v102, 0
	v_mov_b32_e32 v103, 0
	v_mov_b32_e32 v104, 0
	v_mov_b32_e32 v105, 0
	v_mov_b32_e32 v106, 0
	v_mov_b32_e32 v107, 0
	v_mov_b32_e32 v108, 0
	v_mov_b32_e32 v109, 0
	v_mov_b32_e32 v110, 0
	v_mov_b32_e32 v111, 0
	v_mov_b32_e32 v32, 0
	v_mov_b32_e32 v33, 0
	v_mov_b32_e32 v34, 0
	v_mov_b32_e32 v35, 0
	v_mov_b32_e32 v36, 0
	v_mov_b32_e32 v37, 0
	v_mov_b32_e32 v38, 0
	v_mov_b32_e32 v39, 0
	v_mov_b32_e32 v40, 0
	v_mov_b32_e32 v41, 0
	v_mov_b32_e32 v42, 0
	v_mov_b32_e32 v43, 0
	v_mov_b32_e32 v44, 0
	v_mov_b32_e32 v45, 0
	v_mov_b32_e32 v46, 0
	v_mov_b32_e32 v47, 0
	v_mov_b32_e32 v80, 0
	v_mov_b32_e32 v81, 0
	v_mov_b32_e32 v82, 0
	v_mov_b32_e32 v83, 0
	v_mov_b32_e32 v84, 0
	v_mov_b32_e32 v85, 0
	v_mov_b32_e32 v86, 0
	v_mov_b32_e32 v87, 0
	v_mov_b32_e32 v88, 0
	v_mov_b32_e32 v89, 0
	v_mov_b32_e32 v90, 0
	v_mov_b32_e32 v91, 0
	v_mov_b32_e32 v92, 0
	v_mov_b32_e32 v93, 0
	v_mov_b32_e32 v94, 0
	v_mov_b32_e32 v95, 0
	v_mov_b32_e32 v16, 0
	v_mov_b32_e32 v17, 0
	v_mov_b32_e32 v18, 0
	v_mov_b32_e32 v19, 0
	v_mov_b32_e32 v20, 0
	v_mov_b32_e32 v21, 0
	v_mov_b32_e32 v22, 0
	v_mov_b32_e32 v23, 0
	v_mov_b32_e32 v24, 0
	v_mov_b32_e32 v25, 0
	v_mov_b32_e32 v26, 0
	v_mov_b32_e32 v27, 0
	v_mov_b32_e32 v28, 0
	v_mov_b32_e32 v29, 0
	v_mov_b32_e32 v30, 0
	v_mov_b32_e32 v31, 0
	v_mov_b32_e32 v64, 0
	v_mov_b32_e32 v65, 0
	v_mov_b32_e32 v66, 0
	v_mov_b32_e32 v67, 0
	v_mov_b32_e32 v68, 0
	v_mov_b32_e32 v69, 0
	v_mov_b32_e32 v70, 0
	v_mov_b32_e32 v71, 0
	v_mov_b32_e32 v72, 0
	v_mov_b32_e32 v73, 0
	v_mov_b32_e32 v74, 0
	v_mov_b32_e32 v75, 0
	v_mov_b32_e32 v76, 0
	v_mov_b32_e32 v77, 0
	v_mov_b32_e32 v78, 0
	v_mov_b32_e32 v79, 0
	v_mov_b32_e32 v0, 0
	v_mov_b32_e32 v1, 0
	v_mov_b32_e32 v2, 0
	v_mov_b32_e32 v3, 0
	v_mov_b32_e32 v4, 0
	v_mov_b32_e32 v5, 0
	v_mov_b32_e32 v6, 0
	v_mov_b32_e32 v7, 0
	v_mov_b32_e32 v8, 0
	v_mov_b32_e32 v9, 0
	v_mov_b32_e32 v10, 0
	v_mov_b32_e32 v11, 0
	v_mov_b32_e32 v12, 0
	v_mov_b32_e32 v13, 0
	v_mov_b32_e32 v14, 0
	v_mov_b32_e32 v15, 0
	s_waitcnt vmcnt(8)
	s_barrier
	ds_read_b128 v[230:233], v248 offset:16384
	ds_read_b128 v[214:217], v246
	ds_read_b128 v[234:237], v248 offset:18432
	ds_read_b128 v[218:221], v246 offset:2048
	ds_read_b128 v[222:225], v246 offset:4096
	s_mov_b32 s73, 8
.Lg4_loop:
	s_waitcnt vmcnt(4)
	s_barrier
	s_add_i32 m0, s72, 0x18000
	s_waitcnt lgkmcnt(3)
	v_mfma_f32_32x32x16_bf16 v[112:127], v[214:217], v[230:233], v[112:127]
	global_load_lds_dwordx4 v198, s[66:67]
	s_waitcnt lgkmcnt(2)
	v_mfma_f32_32x32x16_bf16 v[48:63], v[214:217], v[234:237], v[48:63]
	ds_read_b128 v[226:229], v246 offset:6144
	ds_read_b128 v[238:241], v249 offset:16384
	s_add_i32 m0, s72, 0x1c000
	s_waitcnt lgkmcnt(3)
	v_mfma_f32_32x32x16_bf16 v[96:111], v[218:221], v[230:233], v[96:111]
	global_load_lds_dwordx4 v198, s[70:71]
	v_mfma_f32_32x32x16_bf16 v[32:47], v[218:221], v[234:237], v[32:47]
	ds_read_b128 v[214:217], v247
	ds_read_b128 v[242:245], v249 offset:18432
	s_add_i32 m0, s72, 0x1a000
	s_waitcnt lgkmcnt(4)
	v_mfma_f32_32x32x16_bf16 v[80:95], v[222:225], v[230:233], v[80:95]
	global_load_lds_dwordx4 v199, s[66:67]
	v_mfma_f32_32x32x16_bf16 v[16:31], v[222:225], v[234:237], v[16:31]
	ds_read_b128 v[218:221], v247 offset:2048
	s_add_i32 m0, s72, 0x1e000
	s_waitcnt lgkmcnt(4)
	v_mfma_f32_32x32x16_bf16 v[64:79], v[226:229], v[230:233], v[64:79]
	global_load_lds_dwordx4 v199, s[70:71]
	v_mfma_f32_32x32x16_bf16 v[0:15], v[226:229], v[234:237], v[0:15]
	s_add_u32 s66, s66, 64
	s_addc_u32 s67, s67, 0
	s_add_u32 s70, s70, 64
	s_addc_u32 s71, s71, 0
	ds_read_b128 v[222:225], v247 offset:4096
	s_waitcnt lgkmcnt(3)
	v_mfma_f32_32x32x16_bf16 v[112:127], v[214:217], v[238:241], v[112:127]
	s_waitcnt lgkmcnt(2)
	v_mfma_f32_32x32x16_bf16 v[48:63], v[214:217], v[242:245], v[48:63]
	ds_read_b128 v[226:229], v247 offset:6144
	ds_read_b128 v[230:233], v248 offset:49152
	s_waitcnt lgkmcnt(3)
	v_mfma_f32_32x32x16_bf16 v[96:111], v[218:221], v[238:241], v[96:111]
	v_mfma_f32_32x32x16_bf16 v[32:47], v[218:221], v[242:245], v[32:47]
	ds_read_b128 v[214:217], v246 offset:32768
	ds_read_b128 v[234:237], v248 offset:51200
	s_waitcnt lgkmcnt(4)
	v_mfma_f32_32x32x16_bf16 v[80:95], v[222:225], v[238:241], v[80:95]
	v_mfma_f32_32x32x16_bf16 v[16:31], v[222:225], v[242:245], v[16:31]
	ds_read_b128 v[218:221], v246 offset:34816
	s_waitcnt lgkmcnt(4)
	v_mfma_f32_32x32x16_bf16 v[64:79], v[226:229], v[238:241], v[64:79]
	v_mfma_f32_32x32x16_bf16 v[0:15], v[226:229], v[242:245], v[0:15]
	ds_read_b128 v[222:225], v246 offset:36864
	s_add_i32 s73, s73, -1
	s_cmp_eq_u32 s73, 0
	s_cbranch_scc1 .Lg4_tail
	s_waitcnt vmcnt(4)
	s_barrier
	s_add_i32 m0, s72, 0x0
	s_waitcnt lgkmcnt(3)
	v_mfma_f32_32x32x16_bf16 v[112:127], v[214:217], v[230:233], v[112:127]
	global_load_lds_dwordx4 v198, s[66:67]
	s_waitcnt lgkmcnt(2)
	v_mfma_f32_32x32x16_bf16 v[48:63], v[214:217], v[234:237], v[48:63]
	ds_read_b128 v[226:229], v246 offset:38912
	ds_read_b128 v[238:241], v249 offset:49152
	s_add_i32 m0, s72, 0x4000
	s_waitcnt lgkmcnt(3)
	v_mfma_f32_32x32x16_bf16 v[96:111], v[218:221], v[230:233], v[96:111]
	global_load_lds_dwordx4 v198, s[70:71]
	v_mfma_f32_32x32x16_bf16 v[32:47], v[218:221], v[234:237], v[32:47]
	ds_read_b128 v[214:217], v247 offset:32768
	ds_read_b128 v[242:245], v249 offset:51200
	s_add_i32 m0, s72, 0x2000
	s_waitcnt lgkmcnt(4)
	v_mfma_f32_32x32x16_bf16 v[80:95], v[222:225], v[230:233], v[80:95]
	global_load_lds_dwordx4 v199, s[66:67]
	v_mfma_f32_32x32x16_bf16 v[16:31], v[222:225], v[234:237], v[16:31]
	ds_read_b128 v[218:221], v247 offset:34816
	s_add_i32 m0, s72, 0x6000
	s_waitcnt lgkmcnt(4)
	v_mfma_f32_32x32x16_bf16 v[64:79], v[226:229], v[230:233], v[64:79]
	global_load_lds_dwordx4 v199, s[70:71]
	v_mfma_f32_32x32x16_bf16 v[0:15], v[226:229], v[234:237], v[0:15]
	s_add_u32 s66, s66, 64
	s_addc_u32 s67, s67, 0
	s_add_u32 s70, s70, 64
	s_addc_u32 s71, s71, 0
	ds_read_b128 v[222:225], v247 offset:36864
	s_waitcnt lgkmcnt(3)
	v_mfma_f32_32x32x16_bf16 v[112:127], v[214:217], v[238:241], v[112:127]
	s_waitcnt lgkmcnt(2)
	v_mfma_f32_32x32x16_bf16 v[48:63], v[214:217], v[242:245], v[48:63]
	ds_read_b128 v[226:229], v247 offset:38912
	ds_read_b128 v[230:233], v252 offset:16384
	s_waitcnt lgkmcnt(3)
	v_mfma_f32_32x32x16_bf16 v[96:111], v[218:221], v[238:241], v[96:111]
	v_mfma_f32_32x32x16_bf16 v[32:47], v[218:221], v[242:245], v[32:47]
	ds_read_b128 v[214:217], v250
	ds_read_b128 v[234:237], v252 offset:18432
	s_waitcnt lgkmcnt(4)
	v_mfma_f32_32x32x16_bf16 v[80:95], v[222:225], v[238:241], v[80:95]
	v_mfma_f32_32x32x16_bf16 v[16:31], v[222:225], v[242:245], v[16:31]
	ds_read_b128 v[218:221], v250 offset:2048
	s_waitcnt lgkmcnt(4)
	v_mfma_f32_32x32x16_bf16 v[64:79], v[226:229], v[238:241], v[64:79]
	v_mfma_f32_32x32x16_bf16 v[0:15], v[226:229], v[242:245], v[0:15]
	ds_read_b128 v[222:225], v250 offset:4096
	s_waitcnt vmcnt(4)
	s_barrier
	s_add_i32 m0, s72, 0x8000
	s_waitcnt lgkmcnt(3)
	v_mfma_f32_32x32x16_bf16 v[112:127], v[214:217], v[230:233], v[112:127]
	global_load_lds_dwordx4 v198, s[66:67]
	s_waitcnt lgkmcnt(2)
	v_mfma_f32_32x32x16_bf16 v[48:63], v[214:217], v[234:237], v[48:63]
	ds_read_b128 v[226:229], v250 offset:6144
	ds_read_b128 v[238:241], v253 offset:16384
	s_add_i32 m0, s72, 0xc000
	s_waitcnt lgkmcnt(3)
	v_mfma_f32_32x32x16_bf16 v[96:111], v[218:221], v[230:233], v[96:111]
	global_load_lds_dwordx4 v198, s[70:71]
	v_mfma_f32_32x32x16_bf16 v[32:47], v[218:221], v[234:237], v[32:47]
	ds_read_b128 v[214:217], v251
	ds_read_b128 v[242:245], v253 offset:18432
	s_add_i32 m0, s72, 0xa000
	s_waitcnt lgkmcnt(4)
	v_mfma_f32_32x32x16_bf16 v[80:95], v[222:225], v[230:233], v[80:95]
	global_load_lds_dwordx4 v199, s[66:67]
	v_mfma_f32_32x32x16_bf16 v[16:31], v[222:225], v[234:237], v[16:31]
	ds_read_b128 v[218:221], v251 offset:2048
	s_add_i32 m0, s72, 0xe000
	s_waitcnt lgkmcnt(4)
	v_mfma_f32_32x32x16_bf16 v[64:79], v[226:229], v[230:233], v[64:79]
	global_load_lds_dwordx4 v199, s[70:71]
	v_mfma_f32_32x32x16_bf16 v[0:15], v[226:229], v[234:237], v[0:15]
	s_add_u32 s66, s66, 64
	s_addc_u32 s67, s67, 0
	s_add_u32 s70, s70, 64
	s_addc_u32 s71, s71, 0
	ds_read_b128 v[222:225], v251 offset:4096
	s_waitcnt lgkmcnt(3)
	v_mfma_f32_32x32x16_bf16 v[112:127], v[214:217], v[238:241], v[112:127]
	s_waitcnt lgkmcnt(2)
	v_mfma_f32_32x32x16_bf16 v[48:63], v[214:217], v[242:245], v[48:63]
	ds_read_b128 v[226:229], v251 offset:6144
	ds_read_b128 v[230:233], v252 offset:49152
	s_waitcnt lgkmcnt(3)
	v_mfma_f32_32x32x16_bf16 v[96:111], v[218:221], v[238:241], v[96:111]
	v_mfma_f32_32x32x16_bf16 v[32:47], v[218:221], v[242:245], v[32:47]
	ds_read_b128 v[214:217], v250 offset:32768
	ds_read_b128 v[234:237], v252 offset:51200
	s_waitcnt lgkmcnt(4)
	v_mfma_f32_32x32x16_bf16 v[80:95], v[222:225], v[238:241], v[80:95]
	v_mfma_f32_32x32x16_bf16 v[16:31], v[222:225], v[242:245], v[16:31]
	ds_read_b128 v[218:221], v250 offset:34816
	s_waitcnt lgkmcnt(4)
	v_mfma_f32_32x32x16_bf16 v[64:79], v[226:229], v[238:241], v[64:79]
	v_mfma_f32_32x32x16_bf16 v[0:15], v[226:229], v[242:245], v[0:15]
	ds_read_b128 v[222:225], v250 offset:36864
	s_waitcnt vmcnt(4)
	s_barrier
	s_add_i32 m0, s72, 0x10000
	s_waitcnt lgkmcnt(3)
	v_mfma_f32_32x32x16_bf16 v[112:127], v[214:217], v[230:233], v[112:127]
	global_load_lds_dwordx4 v198, s[66:67]
	s_waitcnt lgkmcnt(2)
	v_mfma_f32_32x32x16_bf16 v[48:63], v[214:217], v[234:237], v[48:63]
	ds_read_b128 v[226:229], v250 offset:38912
	ds_read_b128 v[238:241], v253 offset:49152
	s_add_i32 m0, s72, 0x14000
	s_waitcnt lgkmcnt(3)
	v_mfma_f32_32x32x16_bf16 v[96:111], v[218:221], v[230:233], v[96:111]
	global_load_lds_dwordx4 v198, s[70:71]
	v_mfma_f32_32x32x16_bf16 v[32:47], v[218:221], v[234:237], v[32:47]
	ds_read_b128 v[214:217], v251 offset:32768
	ds_read_b128 v[242:245], v253 offset:51200
	s_add_i32 m0, s72, 0x12000
	s_waitcnt lgkmcnt(4)
	v_mfma_f32_32x32x16_bf16 v[80:95], v[222:225], v[230:233], v[80:95]
	global_load_lds_dwordx4 v199, s[66:67]
	v_mfma_f32_32x32x16_bf16 v[16:31], v[222:225], v[234:237], v[16:31]
	ds_read_b128 v[218:221], v251 offset:34816
	s_add_i32 m0, s72, 0x16000
	s_waitcnt lgkmcnt(4)
	v_mfma_f32_32x32x16_bf16 v[64:79], v[226:229], v[230:233], v[64:79]
	global_load_lds_dwordx4 v199, s[70:71]
	v_mfma_f32_32x32x16_bf16 v[0:15], v[226:229], v[234:237], v[0:15]
	s_add_u32 s66, s66, 64
	s_addc_u32 s67, s67, 0
	s_add_u32 s70, s70, 64
	s_addc_u32 s71, s71, 0
	ds_read_b128 v[222:225], v251 offset:36864
	s_waitcnt lgkmcnt(3)
	v_mfma_f32_32x32x16_bf16 v[112:127], v[214:217], v[238:241], v[112:127]
	s_waitcnt lgkmcnt(2)
	v_mfma_f32_32x32x16_bf16 v[48:63], v[214:217], v[242:245], v[48:63]
	ds_read_b128 v[226:229], v251 offset:38912
	ds_read_b128 v[230:233], v248 offset:16384
	s_waitcnt lgkmcnt(3)
	v_mfma_f32_32x32x16_bf16 v[96:111], v[218:221], v[238:241], v[96:111]
	v_mfma_f32_32x32x16_bf16 v[32:47], v[218:221], v[242:245], v[32:47]
	ds_read_b128 v[214:217], v246
	ds_read_b128 v[234:237], v248 offset:18432
	s_waitcnt lgkmcnt(4)
	v_mfma_f32_32x32x16_bf16 v[80:95], v[222:225], v[238:241], v[80:95]
	v_mfma_f32_32x32x16_bf16 v[16:31], v[222:225], v[242:245], v[16:31]
	ds_read_b128 v[218:221], v246 offset:2048
	s_waitcnt lgkmcnt(4)
	v_mfma_f32_32x32x16_bf16 v[64:79], v[226:229], v[238:241], v[64:79]
	v_mfma_f32_32x32x16_bf16 v[0:15], v[226:229], v[242:245], v[0:15]
	ds_read_b128 v[222:225], v246 offset:4096
	s_branch .Lg4_loop
.Lg4_tail:
	s_waitcnt vmcnt(4)
	s_barrier
	s_waitcnt lgkmcnt(3)
	v_mfma_f32_32x32x16_bf16 v[112:127], v[214:217], v[230:233], v[112:127]
	s_waitcnt lgkmcnt(2)
	v_mfma_f32_32x32x16_bf16 v[48:63], v[214:217], v[234:237], v[48:63]
	ds_read_b128 v[226:229], v246 offset:38912
	ds_read_b128 v[238:241], v249 offset:49152
	s_waitcnt lgkmcnt(3)
	v_mfma_f32_32x32x16_bf16 v[96:111], v[218:221], v[230:233], v[96:111]
	v_mfma_f32_32x32x16_bf16 v[32:47], v[218:221], v[234:237], v[32:47]
	ds_read_b128 v[214:217], v247 offset:32768
	ds_read_b128 v[242:245], v249 offset:51200
	s_waitcnt lgkmcnt(4)
	v_mfma_f32_32x32x16_bf16 v[80:95], v[222:225], v[230:233], v[80:95]
	v_mfma_f32_32x32x16_bf16 v[16:31], v[222:225], v[234:237], v[16:31]
	ds_read_b128 v[218:221], v247 offset:34816
	s_waitcnt lgkmcnt(4)
	v_mfma_f32_32x32x16_bf16 v[64:79], v[226:229], v[230:233], v[64:79]
	v_mfma_f32_32x32x16_bf16 v[0:15], v[226:229], v[234:237], v[0:15]
	ds_read_b128 v[222:225], v247 offset:36864
	s_waitcnt lgkmcnt(3)
	v_mfma_f32_32x32x16_bf16 v[112:127], v[214:217], v[238:241], v[112:127]
	s_waitcnt lgkmcnt(2)
	v_mfma_f32_32x32x16_bf16 v[48:63], v[214:217], v[242:245], v[48:63]
	ds_read_b128 v[226:229], v247 offset:38912
	ds_read_b128 v[230:233], v252 offset:16384
	s_waitcnt lgkmcnt(3)
	v_mfma_f32_32x32x16_bf16 v[96:111], v[218:221], v[238:241], v[96:111]
	v_mfma_f32_32x32x16_bf16 v[32:47], v[218:221], v[242:245], v[32:47]
	ds_read_b128 v[214:217], v250
	ds_read_b128 v[234:237], v252 offset:18432
	s_waitcnt lgkmcnt(4)
	v_mfma_f32_32x32x16_bf16 v[80:95], v[222:225], v[238:241], v[80:95]
	v_mfma_f32_32x32x16_bf16 v[16:31], v[222:225], v[242:245], v[16:31]
	ds_read_b128 v[218:221], v250 offset:2048
	s_waitcnt lgkmcnt(4)
	v_mfma_f32_32x32x16_bf16 v[64:79], v[226:229], v[238:241], v[64:79]
	v_mfma_f32_32x32x16_bf16 v[0:15], v[226:229], v[242:245], v[0:15]
	ds_read_b128 v[222:225], v250 offset:4096
	s_waitcnt vmcnt(0)
	s_barrier
	s_waitcnt lgkmcnt(3)
	v_mfma_f32_32x32x16_bf16 v[112:127], v[214:217], v[230:233], v[112:127]
	s_waitcnt lgkmcnt(2)
	v_mfma_f32_32x32x16_bf16 v[48:63], v[214:217], v[234:237], v[48:63]
	ds_read_b128 v[226:229], v250 offset:6144
	ds_read_b128 v[238:241], v253 offset:16384
	s_waitcnt lgkmcnt(3)
	v_mfma_f32_32x32x16_bf16 v[96:111], v[218:221], v[230:233], v[96:111]
	v_mfma_f32_32x32x16_bf16 v[32:47], v[218:221], v[234:237], v[32:47]
	ds_read_b128 v[214:217], v251
	ds_read_b128 v[242:245], v253 offset:18432
	s_waitcnt lgkmcnt(4)
	v_mfma_f32_32x32x16_bf16 v[80:95], v[222:225], v[230:233], v[80:95]
	v_mfma_f32_32x32x16_bf16 v[16:31], v[222:225], v[234:237], v[16:31]
	ds_read_b128 v[218:221], v251 offset:2048
	s_waitcnt lgkmcnt(4)
	v_mfma_f32_32x32x16_bf16 v[64:79], v[226:229], v[230:233], v[64:79]
	v_mfma_f32_32x32x16_bf16 v[0:15], v[226:229], v[234:237], v[0:15]
	ds_read_b128 v[222:225], v251 offset:4096
	s_waitcnt lgkmcnt(3)
	v_mfma_f32_32x32x16_bf16 v[112:127], v[214:217], v[238:241], v[112:127]
	s_waitcnt lgkmcnt(2)
	v_mfma_f32_32x32x16_bf16 v[48:63], v[214:217], v[242:245], v[48:63]
	ds_read_b128 v[226:229], v251 offset:6144
	ds_read_b128 v[230:233], v252 offset:49152
	s_waitcnt lgkmcnt(3)
	v_mfma_f32_32x32x16_bf16 v[96:111], v[218:221], v[238:241], v[96:111]
	v_mfma_f32_32x32x16_bf16 v[32:47], v[218:221], v[242:245], v[32:47]
	ds_read_b128 v[214:217], v250 offset:32768
	ds_read_b128 v[234:237], v252 offset:51200
	s_waitcnt lgkmcnt(4)
	v_mfma_f32_32x32x16_bf16 v[80:95], v[222:225], v[238:241], v[80:95]
	v_mfma_f32_32x32x16_bf16 v[16:31], v[222:225], v[242:245], v[16:31]
	ds_read_b128 v[218:221], v250 offset:34816
	s_waitcnt lgkmcnt(4)
	v_mfma_f32_32x32x16_bf16 v[64:79], v[226:229], v[238:241], v[64:79]
	v_mfma_f32_32x32x16_bf16 v[0:15], v[226:229], v[242:245], v[0:15]
	ds_read_b128 v[222:225], v250 offset:36864
	s_waitcnt lgkmcnt(3)
	v_mfma_f32_32x32x16_bf16 v[112:127], v[214:217], v[230:233], v[112:127]
	s_waitcnt lgkmcnt(2)
	v_mfma_f32_32x32x16_bf16 v[48:63], v[214:217], v[234:237], v[48:63]
	ds_read_b128 v[226:229], v250 offset:38912
	ds_read_b128 v[238:241], v253 offset:49152
	s_waitcnt lgkmcnt(3)
	v_mfma_f32_32x32x16_bf16 v[96:111], v[218:221], v[230:233], v[96:111]
	v_mfma_f32_32x32x16_bf16 v[32:47], v[218:221], v[234:237], v[32:47]
	ds_read_b128 v[214:217], v251 offset:32768
	ds_read_b128 v[242:245], v253 offset:51200
	s_waitcnt lgkmcnt(4)
	v_mfma_f32_32x32x16_bf16 v[80:95], v[222:225], v[230:233], v[80:95]
	v_mfma_f32_32x32x16_bf16 v[16:31], v[222:225], v[234:237], v[16:31]
	ds_read_b128 v[218:221], v251 offset:34816
	s_waitcnt lgkmcnt(4)
	v_mfma_f32_32x32x16_bf16 v[64:79], v[226:229], v[230:233], v[64:79]
	v_mfma_f32_32x32x16_bf16 v[0:15], v[226:229], v[234:237], v[0:15]
	ds_read_b128 v[222:225], v251 offset:36864
	s_waitcnt lgkmcnt(3)
	v_mfma_f32_32x32x16_bf16 v[112:127], v[214:217], v[238:241], v[112:127]
	s_waitcnt lgkmcnt(2)
	v_mfma_f32_32x32x16_bf16 v[48:63], v[214:217], v[242:245], v[48:63]
	ds_read_b128 v[226:229], v251 offset:38912
	s_waitcnt lgkmcnt(2)
	v_mfma_f32_32x32x16_bf16 v[96:111], v[218:221], v[238:241], v[96:111]
	v_mfma_f32_32x32x16_bf16 v[32:47], v[218:221], v[242:245], v[32:47]
	s_waitcnt lgkmcnt(1)
	v_mfma_f32_32x32x16_bf16 v[80:95], v[222:225], v[238:241], v[80:95]
	v_mfma_f32_32x32x16_bf16 v[16:31], v[222:225], v[242:245], v[16:31]
	s_waitcnt lgkmcnt(0)
	v_mfma_f32_32x32x16_bf16 v[64:79], v[226:229], v[238:241], v[64:79]
	v_mfma_f32_32x32x16_bf16 v[0:15], v[226:229], v[242:245], v[0:15]
	s_barrier
	s_or_b32 s64, s64, s68
	s_nop 10
	v_cvt_pk_bf16_f32 v112, v112, v113
	v_cvt_pk_bf16_f32 v113, v114, v115
	ds_write_b64 v149, v[112:113]
	v_cvt_pk_bf16_f32 v112, v116, v117
	v_cvt_pk_bf16_f32 v113, v118, v119
	ds_write_b64 v150, v[112:113]
	v_cvt_pk_bf16_f32 v112, v120, v121
	v_cvt_pk_bf16_f32 v113, v122, v123
	ds_write_b64 v151, v[112:113]
	v_cvt_pk_bf16_f32 v112, v124, v125
	v_cvt_pk_bf16_f32 v113, v126, v127
	v_cvt_pk_bf16_f32 v96, v96, v97
	v_cvt_pk_bf16_f32 v97, v98, v99
	ds_write_b64 v152, v[112:113]
	ds_write_b64 v153, v[96:97]
	v_cvt_pk_bf16_f32 v96, v100, v101
	v_cvt_pk_bf16_f32 v97, v102, v103
	ds_write_b64 v154, v[96:97]
	v_cvt_pk_bf16_f32 v96, v104, v105
	v_cvt_pk_bf16_f32 v97, v106, v107
	ds_write_b64 v155, v[96:97]
	v_cvt_pk_bf16_f32 v96, v108, v109
	v_cvt_pk_bf16_f32 v97, v110, v111
	v_cvt_pk_bf16_f32 v80, v80, v81
	v_cvt_pk_bf16_f32 v81, v82, v83
	ds_write_b64 v156, v[96:97]
	ds_write_b64 v157, v[80:81]
	v_cvt_pk_bf16_f32 v80, v84, v85
	v_cvt_pk_bf16_f32 v81, v86, v87
	ds_write_b64 v158, v[80:81]
	v_cvt_pk_bf16_f32 v80, v88, v89
	v_cvt_pk_bf16_f32 v81, v90, v91
	ds_write_b64 v159, v[80:81]
	v_cvt_pk_bf16_f32 v80, v92, v93
	v_cvt_pk_bf16_f32 v81, v94, v95
	v_cvt_pk_bf16_f32 v64, v64, v65
	v_cvt_pk_bf16_f32 v65, v66, v67
	ds_write_b64 v160, v[80:81]
	ds_write_b64 v161, v[64:65]
	v_cvt_pk_bf16_f32 v64, v68, v69
	v_cvt_pk_bf16_f32 v65, v70, v71
	ds_write_b64 v162, v[64:65]
	v_cvt_pk_bf16_f32 v64, v72, v73
	v_cvt_pk_bf16_f32 v65, v74, v75
	ds_write_b64 v163, v[64:65]
	v_cvt_pk_bf16_f32 v64, v76, v77
	v_cvt_pk_bf16_f32 v65, v78, v79
	v_cvt_pk_bf16_f32 v48, v48, v49
	v_cvt_pk_bf16_f32 v49, v50, v51
	ds_write_b64 v164, v[64:65]
	ds_write_b64 v165, v[48:49] offset:16384
	v_cvt_pk_bf16_f32 v48, v52, v53
	v_cvt_pk_bf16_f32 v49, v54, v55
	ds_write_b64 v166, v[48:49] offset:16384
	v_cvt_pk_bf16_f32 v48, v56, v57
	v_cvt_pk_bf16_f32 v49, v58, v59
	ds_write_b64 v167, v[48:49] offset:16384
	v_cvt_pk_bf16_f32 v48, v60, v61
	v_cvt_pk_bf16_f32 v49, v62, v63
	v_cvt_pk_bf16_f32 v32, v32, v33
	v_cvt_pk_bf16_f32 v33, v34, v35
	ds_write_b64 v168, v[48:49] offset:16384
	ds_write_b64 v169, v[32:33] offset:16384
	v_cvt_pk_bf16_f32 v32, v36, v37
	v_cvt_pk_bf16_f32 v33, v38, v39
	ds_write_b64 v170, v[32:33] offset:16384
	v_cvt_pk_bf16_f32 v32, v40, v41
	v_cvt_pk_bf16_f32 v33, v42, v43
	ds_write_b64 v171, v[32:33] offset:16384
	v_cvt_pk_bf16_f32 v32, v44, v45
	v_cvt_pk_bf16_f32 v33, v46, v47
	v_cvt_pk_bf16_f32 v16, v16, v17
	v_cvt_pk_bf16_f32 v17, v18, v19
	ds_write_b64 v172, v[32:33] offset:16384
	ds_write_b64 v173, v[16:17] offset:16384
	v_cvt_pk_bf16_f32 v16, v20, v21
	v_cvt_pk_bf16_f32 v17, v22, v23
	ds_write_b64 v174, v[16:17] offset:16384
	v_cvt_pk_bf16_f32 v16, v24, v25
	v_cvt_pk_bf16_f32 v17, v26, v27
	ds_write_b64 v175, v[16:17] offset:16384
	v_cvt_pk_bf16_f32 v16, v28, v29
	v_cvt_pk_bf16_f32 v17, v30, v31
	v_cvt_pk_bf16_f32 v0, v0, v1
	v_cvt_pk_bf16_f32 v1, v2, v3
	ds_write_b64 v176, v[16:17] offset:16384
	ds_write_b64 v177, v[0:1] offset:16384
	v_cvt_pk_bf16_f32 v0, v4, v5
	v_cvt_pk_bf16_f32 v1, v6, v7
	ds_write_b64 v178, v[0:1] offset:16384
	v_cvt_pk_bf16_f32 v0, v8, v9
	v_cvt_pk_bf16_f32 v1, v10, v11
	ds_write_b64 v179, v[0:1] offset:16384
	v_cvt_pk_bf16_f32 v0, v12, v13
	v_cvt_pk_bf16_f32 v1, v14, v15
	ds_write_b64 v180, v[0:1] offset:16384
	v_lshl_add_u64 v[0:1], v[130:131], 0, s[64:65]
	v_lshl_add_u64 v[2:3], v[132:133], 0, s[64:65]
	v_mov_b32_e32 v4, v148
	s_mov_b32 s64, 0
	s_waitcnt vmcnt(0) lgkmcnt(0)
	s_barrier
